# attention steady loop: first four PV MFMAs interleaved into the row-max chain (fills the matrix pipe during the QK->PV transition)
# speedup vs baseline: 1.0001x; 1.0001x over previous
.LBB0_1277:
	s_lshl_b32 s18, s23, 1
	v_mfma_f32_32x32x16_bf16 v[112:127], v[188:191], v[156:159], v[238:253]
	v_add_u32_e32 v237, s18, v214
	ds_read_b64_tr_b16 v[192:193], v237 offset:24576
	v_add_f32_e32 v128, v80, v81
	v_add_f32_e32 v128, v82, v128
	v_add_f32_e32 v128, v83, v128
	v_add_f32_e32 v128, v84, v128
	v_add_f32_e32 v128, v85, v128
	v_cvt_pk_bf16_f32 v148, v80, v81
	v_cvt_pk_bf16_f32 v149, v82, v83
	ds_read_b64_tr_b16 v[194:195], v237 offset:25088
	s_waitcnt lgkmcnt(8)
	v_mfma_f32_32x32x16_bf16 v[96:111], v[184:187], v[156:159], v[238:253]
	v_add_f32_e32 v80, v86, v128
	v_add_f32_e32 v80, v87, v80
	v_add_f32_e32 v80, v88, v80
	v_add_f32_e32 v82, v89, v80
	v_cvt_pk_bf16_f32 v150, v84, v85
	v_cvt_pk_bf16_f32 v151, v86, v87
	ds_read_b64_tr_b16 v[80:81], v237 offset:28672
	s_waitcnt lgkmcnt(8)
	v_mfma_f32_32x32x16_bf16 v[112:127], v[180:183], v[152:155], v[112:127]
	v_add_f32_e32 v82, v90, v82
	v_add_f32_e32 v82, v91, v82
	v_add_f32_e32 v82, v92, v82
	v_add_f32_e32 v84, v93, v82
	v_cvt_pk_bf16_f32 v140, v88, v89
	v_cvt_pk_bf16_f32 v141, v90, v91
	ds_read_b64_tr_b16 v[82:83], v237 offset:29184
	s_waitcnt lgkmcnt(8)
	v_mfma_f32_32x32x16_bf16 v[96:111], v[176:179], v[152:155], v[96:111]
	v_add_f32_e32 v84, v94, v84
	v_add_f32_e32 v84, v95, v84
	v_add_f32_e32 v84, v64, v84
	v_add_f32_e32 v86, v65, v84
	v_cvt_pk_bf16_f32 v142, v92, v93
	v_cvt_pk_bf16_f32 v143, v94, v95
	ds_read_b64_tr_b16 v[84:85], v237 offset:32768
	s_waitcnt lgkmcnt(8)
	v_mfma_f32_32x32x16_bf16 v[112:127], v[172:175], v[144:147], v[112:127]
	v_add_f32_e32 v86, v66, v86
	v_add_f32_e32 v86, v67, v86
	v_add_f32_e32 v86, v68, v86
	v_add_f32_e32 v88, v69, v86
	v_cvt_pk_bf16_f32 v132, v64, v65
	v_cvt_pk_bf16_f32 v133, v66, v67
	ds_read_b64_tr_b16 v[86:87], v237 offset:33280
	s_waitcnt lgkmcnt(8)
	v_mfma_f32_32x32x16_bf16 v[96:111], v[168:171], v[144:147], v[96:111]
	v_add_f32_e32 v64, v70, v88
	v_add_f32_e32 v64, v71, v64
	v_add_f32_e32 v64, v72, v64
	v_add_f32_e32 v66, v73, v64
	v_cvt_pk_bf16_f32 v134, v68, v69
	v_cvt_pk_bf16_f32 v135, v70, v71
	ds_read_b64_tr_b16 v[64:65], v237 offset:36864
	s_waitcnt lgkmcnt(8)
	v_mfma_f32_32x32x16_bf16 v[112:127], v[164:167], v[136:139], v[112:127]
	v_add_f32_e32 v66, v74, v66
	v_add_f32_e32 v66, v75, v66
	v_add_f32_e32 v66, v76, v66
	v_add_f32_e32 v68, v77, v66
	v_cvt_pk_bf16_f32 v128, v72, v73
	v_cvt_pk_bf16_f32 v129, v74, v75
	ds_read_b64_tr_b16 v[66:67], v237 offset:37376
	s_waitcnt lgkmcnt(8)
	v_mfma_f32_32x32x16_bf16 v[96:111], v[160:163], v[136:139], v[96:111]
	v_add_f32_e32 v68, v78, v68
	v_add_f32_e32 v68, v79, v68
	v_add_f32_e32 v236, v236, v68
	v_cvt_pk_bf16_f32 v130, v76, v77
	v_cvt_pk_bf16_f32 v131, v78, v79
	s_add_u32 s30, s98, 0xffffe000
	s_addc_u32 s31, s99, -1
	s_add_i32 s18, s86, s89
	s_nop 0
	s_mov_b32 s23, m0
	s_mov_b32 m0, s18
	s_nop 0
	global_load_lds_dwordx4 v196, s[30:31]
	s_mov_b32 m0, s23
	s_add_u32 s30, s100, 0xffffc000
	s_addc_u32 s31, s101, -1
	s_lshl_b32 s18, s37, 1
	s_add_i32 s18, s18, s90
	s_mov_b32 s23, m0
	s_mov_b32 m0, s18
	s_nop 0
	global_load_lds_dwordx4 v196, s[30:31]
	s_mov_b32 m0, s23
	s_add_u32 s30, s100, 0xffffe000
	s_addc_u32 s31, s101, -1
	s_addk_i32 s18, 0x2000
	s_mov_b32 s23, m0
	s_mov_b32 m0, s18
	s_nop 0
	global_load_lds_dwordx4 v196, s[30:31]
	s_mov_b32 m0, s23
	s_waitcnt lgkmcnt(6)
	v_mfma_f32_32x32x16_bf16 v[32:47], v[148:151], v[192:195], v[32:47]
	v_max_f32_e32 v68, v113, v112
	v_max3_f32 v69, v114, v115, v97
	v_max3_f32 v68, v68, v96, v98
	v_max3_f32 v68, v68, v99, v116
	v_max3_f32 v69, v69, v118, v119
	s_waitcnt lgkmcnt(4)
	v_mfma_f32_32x32x16_bf16 v[48:63], v[148:151], v[80:83], v[48:63]
	v_max3_f32 v68, v68, v117, v100
	v_max3_f32 v69, v69, v102, v103
	v_max3_f32 v68, v68, v101, v120
	v_max3_f32 v69, v69, v122, v123
	v_max3_f32 v68, v68, v121, v104
	s_waitcnt lgkmcnt(2)
	v_mfma_f32_32x32x16_bf16 v[16:31], v[148:151], v[84:87], v[16:31]
	v_max3_f32 v69, v69, v106, v107
	v_max3_f32 v68, v68, v105, v124
	v_max3_f32 v69, v69, v126, v127
	v_max3_f32 v68, v68, v125, v108
	v_max3_f32 v69, v69, v110, v111
	s_waitcnt lgkmcnt(0)
	v_mfma_f32_32x32x16_bf16 v[0:15], v[148:151], v[64:67], v[0:15]
	v_max3_f32 v68, v68, v109, v69
	v_cmp_lt_f32_e32 vcc, s71, v68
	s_cmp_lg_u64 vcc, 0
	s_cselect_b64 s[50:51], -1, 0
	s_cbranch_vccnz .LBB0_1285
.LBB0_1278:
	ds_read_b64_tr_b16 v[68:69], v237 offset:25600
	ds_read_b64_tr_b16 v[70:71], v237 offset:26112
	s_waitcnt lgkmcnt(8)
	v_exp_f32_e32 v112, v112
	v_exp_f32_e32 v113, v113
	ds_read_b64_tr_b16 v[72:73], v237 offset:29696
	ds_read_b64_tr_b16 v[74:75], v237 offset:30208
	s_waitcnt lgkmcnt(8)
	v_exp_f32_e32 v114, v114
	v_exp_f32_e32 v115, v115
	ds_read_b64_tr_b16 v[76:77], v237 offset:33792
	ds_read_b64_tr_b16 v[78:79], v237 offset:34304
	s_waitcnt lgkmcnt(8)
	v_exp_f32_e32 v116, v116
	v_exp_f32_e32 v117, v117
	ds_read_b64_tr_b16 v[80:81], v237 offset:37888
	ds_read_b64_tr_b16 v[82:83], v237 offset:38400
	s_waitcnt lgkmcnt(8)
	v_exp_f32_e32 v118, v118
	v_exp_f32_e32 v119, v119
	ds_read_b64_tr_b16 v[64:65], v237 offset:26624
	ds_read_b64_tr_b16 v[66:67], v237 offset:27136
	s_waitcnt lgkmcnt(8)
	v_mfma_f32_32x32x16_bf16 v[32:47], v[140:143], v[68:71], v[32:47]
	v_exp_f32_e32 v120, v120
	v_exp_f32_e32 v121, v121
	ds_read_b64_tr_b16 v[68:69], v237 offset:30720
	ds_read_b64_tr_b16 v[70:71], v237 offset:31232
	s_waitcnt lgkmcnt(8)
	v_mfma_f32_32x32x16_bf16 v[48:63], v[140:143], v[72:75], v[48:63]
	v_exp_f32_e32 v122, v122
	v_exp_f32_e32 v123, v123
	ds_read_b64_tr_b16 v[72:73], v237 offset:34816
	ds_read_b64_tr_b16 v[74:75], v237 offset:35328
	s_waitcnt lgkmcnt(8)
	v_mfma_f32_32x32x16_bf16 v[16:31], v[140:143], v[76:79], v[16:31]
	v_exp_f32_e32 v124, v124
	v_exp_f32_e32 v125, v125
	ds_read_b64_tr_b16 v[76:77], v237 offset:38912
	ds_read_b64_tr_b16 v[78:79], v237 offset:39424
	s_waitcnt lgkmcnt(8)
	v_mfma_f32_32x32x16_bf16 v[0:15], v[140:143], v[80:83], v[0:15]
	v_exp_f32_e32 v126, v126
	v_exp_f32_e32 v127, v127
	ds_read_b64_tr_b16 v[80:81], v237 offset:27648
	ds_read_b64_tr_b16 v[82:83], v237 offset:28160
	s_waitcnt lgkmcnt(8)
	v_mfma_f32_32x32x16_bf16 v[32:47], v[132:135], v[64:67], v[32:47]
	v_exp_f32_e32 v96, v96
	v_exp_f32_e32 v97, v97
	ds_read_b64_tr_b16 v[64:65], v237 offset:31744
	ds_read_b64_tr_b16 v[66:67], v237 offset:32256
	s_waitcnt lgkmcnt(8)
	v_mfma_f32_32x32x16_bf16 v[48:63], v[132:135], v[68:71], v[48:63]
	v_exp_f32_e32 v98, v98
	v_exp_f32_e32 v99, v99
	ds_read_b64_tr_b16 v[68:69], v237 offset:35840
	ds_read_b64_tr_b16 v[70:71], v237 offset:36352
	s_waitcnt lgkmcnt(8)
	v_mfma_f32_32x32x16_bf16 v[16:31], v[132:135], v[72:75], v[16:31]
	v_exp_f32_e32 v100, v100
	v_exp_f32_e32 v101, v101
	ds_read_b64_tr_b16 v[72:73], v237 offset:39936
	ds_read_b64_tr_b16 v[74:75], v237 offset:40448
	s_waitcnt lgkmcnt(8)
	v_mfma_f32_32x32x16_bf16 v[0:15], v[132:135], v[76:79], v[0:15]
	v_exp_f32_e32 v102, v102
	v_exp_f32_e32 v103, v103
	v_add_u32_e32 v76, s37, v213
	ds_read_b128 v[192:195], v76
	ds_read_b128 v[188:191], v76 offset:512
	s_waitcnt lgkmcnt(8)
	v_mfma_f32_32x32x16_bf16 v[32:47], v[128:131], v[80:83], v[32:47]
	v_exp_f32_e32 v104, v104
	v_exp_f32_e32 v105, v105
	ds_read_b128 v[184:187], v76 offset:2048
	ds_read_b128 v[176:179], v76 offset:2560
	s_waitcnt lgkmcnt(8)
	v_mfma_f32_32x32x16_bf16 v[48:63], v[128:131], v[64:67], v[48:63]
	v_exp_f32_e32 v106, v106
	v_exp_f32_e32 v107, v107
	ds_read_b128 v[172:175], v76 offset:4096
	ds_read_b128 v[168:171], v76 offset:4608
	s_waitcnt lgkmcnt(8)
	v_mfma_f32_32x32x16_bf16 v[16:31], v[128:131], v[68:71], v[16:31]
	v_exp_f32_e32 v108, v108
	v_exp_f32_e32 v109, v109
	ds_read_b128 v[164:167], v76 offset:6144
	ds_read_b128 v[160:163], v76 offset:6656
	v_exp_f32_e32 v110, v110
	v_exp_f32_e32 v111, v111
	s_waitcnt lgkmcnt(8)
	v_mfma_f32_32x32x16_bf16 v[0:15], v[128:131], v[72:75], v[0:15]
	s_waitcnt vmcnt(3) lgkmcnt(0)
	s_barrier
	s_andn2_b64 vcc, exec, s[50:51]
	s_cbranch_vccnz .LBB0_1280
	s_waitcnt lgkmcnt(0)
	v_add_u32_e32 v76, s49, v216
	ds_read_b128 v[64:67], v76 offset:96
	ds_read_b128 v[68:71], v76 offset:64
	ds_read_b128 v[72:75], v76 offset:32
	ds_read_b128 v[76:79], v76
	s_waitcnt lgkmcnt(3)
	v_pk_mul_f32 v[44:45], v[44:45], v[64:65]
	s_waitcnt lgkmcnt(2)
	v_pk_mul_f32 v[40:41], v[40:41], v[68:69]
	s_waitcnt lgkmcnt(1)
	v_pk_mul_f32 v[36:37], v[36:37], v[72:73]
	v_pk_mul_f32 v[46:47], v[46:47], v[66:67]
	v_pk_mul_f32 v[42:43], v[42:43], v[70:71]
	v_pk_mul_f32 v[38:39], v[38:39], v[74:75]
	s_waitcnt lgkmcnt(0)
	v_pk_mul_f32 v[34:35], v[34:35], v[78:79]
	v_pk_mul_f32 v[32:33], v[32:33], v[76:77]
	v_pk_mul_f32 v[60:61], v[60:61], v[64:65]
	v_pk_mul_f32 v[56:57], v[56:57], v[68:69]
	v_pk_mul_f32 v[52:53], v[52:53], v[72:73]
	v_pk_mul_f32 v[62:63], v[62:63], v[66:67]
	v_pk_mul_f32 v[58:59], v[58:59], v[70:71]
	v_pk_mul_f32 v[54:55], v[54:55], v[74:75]
	v_pk_mul_f32 v[50:51], v[50:51], v[78:79]
	v_pk_mul_f32 v[48:49], v[48:49], v[76:77]
	v_pk_mul_f32 v[28:29], v[28:29], v[64:65]
	v_pk_mul_f32 v[24:25], v[24:25], v[68:69]
	v_pk_mul_f32 v[20:21], v[20:21], v[72:73]
	v_pk_mul_f32 v[30:31], v[30:31], v[66:67]
	v_pk_mul_f32 v[26:27], v[26:27], v[70:71]
	v_pk_mul_f32 v[22:23], v[22:23], v[74:75]
	v_pk_mul_f32 v[18:19], v[18:19], v[78:79]
	v_pk_mul_f32 v[16:17], v[16:17], v[76:77]
	v_pk_mul_f32 v[12:13], v[12:13], v[64:65]
	v_pk_mul_f32 v[8:9], v[8:9], v[68:69]
	v_pk_mul_f32 v[4:5], v[4:5], v[72:73]
	v_pk_mul_f32 v[14:15], v[14:15], v[66:67]
	v_pk_mul_f32 v[10:11], v[10:11], v[70:71]
	v_pk_mul_f32 v[6:7], v[6:7], v[74:75]
	v_pk_mul_f32 v[2:3], v[2:3], v[78:79]
	v_pk_mul_f32 v[0:1], v[0:1], v[76:77]
.LBB0_1280:
	s_add_i32 s18, s37, 0x2000
	s_lshl_b32 s23, s86, 1
	v_mfma_f32_32x32x16_bf16 v[80:95], v[192:195], v[156:159], v[238:253]
	v_add_u32_e32 v237, s23, v214
	ds_read_b64_tr_b16 v[180:181], v237 offset:24576
	s_cmpk_lg_i32 s37, 0x4000
	s_cselect_b32 s86, s18, 0
	v_add_f32_e32 v128, v112, v113
	v_add_f32_e32 v128, v114, v128
	v_add_f32_e32 v128, v115, v128
	v_add_f32_e32 v128, v116, v128
	v_add_f32_e32 v128, v117, v128
	v_cvt_pk_bf16_f32 v148, v112, v113
	v_cvt_pk_bf16_f32 v149, v114, v115
	ds_read_b64_tr_b16 v[182:183], v237 offset:25088
	s_waitcnt lgkmcnt(8)
	v_mfma_f32_32x32x16_bf16 v[64:79], v[188:191], v[156:159], v[238:253]
	v_add_f32_e32 v112, v118, v128
	v_add_f32_e32 v112, v119, v112
	v_add_f32_e32 v112, v120, v112
	v_add_f32_e32 v114, v121, v112
	v_cvt_pk_bf16_f32 v150, v116, v117
	v_cvt_pk_bf16_f32 v151, v118, v119
	ds_read_b64_tr_b16 v[112:113], v237 offset:28672
	s_waitcnt lgkmcnt(8)
	v_mfma_f32_32x32x16_bf16 v[80:95], v[184:187], v[152:155], v[80:95]
	v_add_f32_e32 v114, v122, v114
	v_add_f32_e32 v114, v123, v114
	v_add_f32_e32 v114, v124, v114
	v_add_f32_e32 v116, v125, v114
	v_cvt_pk_bf16_f32 v140, v120, v121
	v_cvt_pk_bf16_f32 v141, v122, v123
	ds_read_b64_tr_b16 v[114:115], v237 offset:29184
	s_waitcnt lgkmcnt(8)
	v_mfma_f32_32x32x16_bf16 v[64:79], v[176:179], v[152:155], v[64:79]
	v_add_f32_e32 v116, v126, v116
	v_add_f32_e32 v116, v127, v116
	v_add_f32_e32 v116, v96, v116
	v_add_f32_e32 v118, v97, v116
	v_cvt_pk_bf16_f32 v142, v124, v125
	v_cvt_pk_bf16_f32 v143, v126, v127
	ds_read_b64_tr_b16 v[116:117], v237 offset:32768
	s_waitcnt lgkmcnt(8)
	v_mfma_f32_32x32x16_bf16 v[80:95], v[172:175], v[144:147], v[80:95]
	v_add_f32_e32 v118, v98, v118
	v_add_f32_e32 v118, v99, v118
	v_add_f32_e32 v118, v100, v118
	v_add_f32_e32 v120, v101, v118
	v_cvt_pk_bf16_f32 v132, v96, v97
	v_cvt_pk_bf16_f32 v133, v98, v99
	ds_read_b64_tr_b16 v[118:119], v237 offset:33280
	s_waitcnt lgkmcnt(8)
	v_mfma_f32_32x32x16_bf16 v[64:79], v[168:171], v[144:147], v[64:79]
	v_add_f32_e32 v96, v102, v120
	v_add_f32_e32 v96, v103, v96
	v_add_f32_e32 v96, v104, v96
	v_add_f32_e32 v98, v105, v96
	v_cvt_pk_bf16_f32 v134, v100, v101
	v_cvt_pk_bf16_f32 v135, v102, v103
	ds_read_b64_tr_b16 v[96:97], v237 offset:36864
	s_waitcnt lgkmcnt(8)
	v_mfma_f32_32x32x16_bf16 v[80:95], v[164:167], v[136:139], v[80:95]
	v_add_f32_e32 v98, v106, v98
	v_add_f32_e32 v98, v107, v98
	v_add_f32_e32 v98, v108, v98
	v_add_f32_e32 v100, v109, v98
	v_cvt_pk_bf16_f32 v128, v104, v105
	v_cvt_pk_bf16_f32 v129, v106, v107
	ds_read_b64_tr_b16 v[98:99], v237 offset:37376
	s_waitcnt lgkmcnt(8)
	v_mfma_f32_32x32x16_bf16 v[64:79], v[160:163], v[136:139], v[64:79]
	v_add_f32_e32 v100, v110, v100
	v_add_f32_e32 v100, v111, v100
	v_add_f32_e32 v236, v236, v100
	v_cvt_pk_bf16_f32 v130, v108, v109
	v_cvt_pk_bf16_f32 v131, v110, v111
	s_add_i32 s18, s37, s89
	s_mov_b32 s23, m0
	s_mov_b32 m0, s18
	s_nop 0
	global_load_lds_dwordx4 v196, s[98:99]
	s_mov_b32 m0, s23
	s_lshl_b32 s18, s86, 1
	s_add_i32 s18, s18, s90
	s_mov_b32 s23, m0
	s_mov_b32 m0, s18
	s_nop 0
	global_load_lds_dwordx4 v196, s[100:101]
	s_mov_b32 m0, s23
	s_add_u32 s30, s100, 0x2000
	s_addc_u32 s31, s101, 0
	s_addk_i32 s18, 0x2000
	s_mov_b32 s23, m0
	s_mov_b32 m0, s18
	s_nop 0
	global_load_lds_dwordx4 v196, s[30:31]
	s_mov_b32 m0, s23
	s_waitcnt lgkmcnt(6)
	v_mfma_f32_32x32x16_bf16 v[32:47], v[148:151], v[180:183], v[32:47]
	v_max_f32_e32 v100, v81, v80
	v_max3_f32 v101, v82, v83, v65
	v_max3_f32 v100, v100, v64, v66
	v_max3_f32 v100, v100, v67, v84
	v_max3_f32 v101, v101, v86, v87
	s_waitcnt lgkmcnt(4)
	v_mfma_f32_32x32x16_bf16 v[48:63], v[148:151], v[112:115], v[48:63]
	v_max3_f32 v100, v100, v85, v68
	v_max3_f32 v101, v101, v70, v71
	v_max3_f32 v100, v100, v69, v88
	v_max3_f32 v101, v101, v90, v91
	v_max3_f32 v100, v100, v89, v72
	s_waitcnt lgkmcnt(2)
	v_mfma_f32_32x32x16_bf16 v[16:31], v[148:151], v[116:119], v[16:31]
	v_max3_f32 v101, v101, v74, v75
	v_max3_f32 v100, v100, v73, v92
	v_max3_f32 v101, v101, v94, v95
	v_max3_f32 v100, v100, v93, v76
	v_max3_f32 v101, v101, v78, v79
	s_waitcnt lgkmcnt(0)
	v_mfma_f32_32x32x16_bf16 v[0:15], v[148:151], v[96:99], v[0:15]
	v_max3_f32 v100, v100, v77, v101
	v_cmp_lt_f32_e32 vcc, s71, v100
	s_cmp_lg_u64 vcc, 0
	s_cselect_b64 s[50:51], -1, 0
	s_cbranch_vccnz .LBB0_1288
.LBB0_1281:
	ds_read_b64_tr_b16 v[100:101], v237 offset:25600
	ds_read_b64_tr_b16 v[102:103], v237 offset:26112
	s_waitcnt lgkmcnt(8)
	v_exp_f32_e32 v80, v80
	v_exp_f32_e32 v81, v81
	ds_read_b64_tr_b16 v[104:105], v237 offset:29696
	ds_read_b64_tr_b16 v[106:107], v237 offset:30208
	s_waitcnt lgkmcnt(8)
	v_exp_f32_e32 v82, v82
	v_exp_f32_e32 v83, v83
	ds_read_b64_tr_b16 v[108:109], v237 offset:33792
	ds_read_b64_tr_b16 v[110:111], v237 offset:34304
	s_waitcnt lgkmcnt(8)
	v_exp_f32_e32 v84, v84
	v_exp_f32_e32 v85, v85
	ds_read_b64_tr_b16 v[112:113], v237 offset:37888
	ds_read_b64_tr_b16 v[114:115], v237 offset:38400
	s_waitcnt lgkmcnt(8)
	v_exp_f32_e32 v86, v86
	v_exp_f32_e32 v87, v87
	ds_read_b64_tr_b16 v[96:97], v237 offset:26624
	ds_read_b64_tr_b16 v[98:99], v237 offset:27136
	s_waitcnt lgkmcnt(8)
	v_mfma_f32_32x32x16_bf16 v[32:47], v[140:143], v[100:103], v[32:47]
	v_exp_f32_e32 v88, v88
	v_exp_f32_e32 v89, v89
	ds_read_b64_tr_b16 v[100:101], v237 offset:30720
	ds_read_b64_tr_b16 v[102:103], v237 offset:31232
	s_waitcnt lgkmcnt(8)
	v_mfma_f32_32x32x16_bf16 v[48:63], v[140:143], v[104:107], v[48:63]
	v_exp_f32_e32 v90, v90
	v_exp_f32_e32 v91, v91
	ds_read_b64_tr_b16 v[104:105], v237 offset:34816
	ds_read_b64_tr_b16 v[106:107], v237 offset:35328
	s_waitcnt lgkmcnt(8)
	v_mfma_f32_32x32x16_bf16 v[16:31], v[140:143], v[108:111], v[16:31]
	v_exp_f32_e32 v92, v92
	v_exp_f32_e32 v93, v93
	ds_read_b64_tr_b16 v[108:109], v237 offset:38912
	ds_read_b64_tr_b16 v[110:111], v237 offset:39424
	s_waitcnt lgkmcnt(8)
	v_mfma_f32_32x32x16_bf16 v[0:15], v[140:143], v[112:115], v[0:15]
	v_exp_f32_e32 v94, v94
	v_exp_f32_e32 v95, v95
	ds_read_b64_tr_b16 v[112:113], v237 offset:27648
	ds_read_b64_tr_b16 v[114:115], v237 offset:28160
	s_waitcnt lgkmcnt(8)
	v_mfma_f32_32x32x16_bf16 v[32:47], v[132:135], v[96:99], v[32:47]
	v_exp_f32_e32 v64, v64
	v_exp_f32_e32 v65, v65
	ds_read_b64_tr_b16 v[96:97], v237 offset:31744
	ds_read_b64_tr_b16 v[98:99], v237 offset:32256
	s_waitcnt lgkmcnt(8)
	v_mfma_f32_32x32x16_bf16 v[48:63], v[132:135], v[100:103], v[48:63]
	v_exp_f32_e32 v66, v66
	v_exp_f32_e32 v67, v67
	ds_read_b64_tr_b16 v[100:101], v237 offset:35840
	ds_read_b64_tr_b16 v[102:103], v237 offset:36352
	s_waitcnt lgkmcnt(8)
	v_mfma_f32_32x32x16_bf16 v[16:31], v[132:135], v[104:107], v[16:31]
	v_exp_f32_e32 v68, v68
	v_exp_f32_e32 v69, v69
	ds_read_b64_tr_b16 v[104:105], v237 offset:39936
	ds_read_b64_tr_b16 v[106:107], v237 offset:40448
	s_waitcnt lgkmcnt(8)
	v_mfma_f32_32x32x16_bf16 v[0:15], v[132:135], v[108:111], v[0:15]
	v_exp_f32_e32 v70, v70
	v_exp_f32_e32 v71, v71
	v_add_u32_e32 v108, s86, v213
	ds_read_b128 v[188:191], v108
	ds_read_b128 v[184:187], v108 offset:512
	s_waitcnt lgkmcnt(8)
	v_mfma_f32_32x32x16_bf16 v[32:47], v[128:131], v[112:115], v[32:47]
	v_exp_f32_e32 v72, v72
	v_exp_f32_e32 v73, v73
	ds_read_b128 v[180:183], v108 offset:2048
	ds_read_b128 v[176:179], v108 offset:2560
	s_waitcnt lgkmcnt(8)
	v_mfma_f32_32x32x16_bf16 v[48:63], v[128:131], v[96:99], v[48:63]
	v_exp_f32_e32 v74, v74
	v_exp_f32_e32 v75, v75
	ds_read_b128 v[172:175], v108 offset:4096
	ds_read_b128 v[168:171], v108 offset:4608
	s_waitcnt lgkmcnt(8)
	v_mfma_f32_32x32x16_bf16 v[16:31], v[128:131], v[100:103], v[16:31]
	v_exp_f32_e32 v76, v76
	v_exp_f32_e32 v77, v77
	ds_read_b128 v[164:167], v108 offset:6144
	ds_read_b128 v[160:163], v108 offset:6656
	v_exp_f32_e32 v78, v78
	v_exp_f32_e32 v79, v79
	s_waitcnt lgkmcnt(8)
	v_mfma_f32_32x32x16_bf16 v[0:15], v[128:131], v[104:107], v[0:15]
	s_waitcnt vmcnt(3) lgkmcnt(0)
	s_barrier
	s_andn2_b64 vcc, exec, s[50:51]
	s_cbranch_vccnz .LBB0_1283
	s_waitcnt lgkmcnt(0)
	v_add_u32_e32 v108, s49, v216
	ds_read_b128 v[96:99], v108 offset:96
	ds_read_b128 v[100:103], v108 offset:64
	ds_read_b128 v[104:107], v108 offset:32
	ds_read_b128 v[108:111], v108
	s_waitcnt lgkmcnt(3)
	v_pk_mul_f32 v[44:45], v[44:45], v[96:97]
	s_waitcnt lgkmcnt(2)
	v_pk_mul_f32 v[40:41], v[40:41], v[100:101]
	s_waitcnt lgkmcnt(1)
	v_pk_mul_f32 v[36:37], v[36:37], v[104:105]
	v_pk_mul_f32 v[46:47], v[46:47], v[98:99]
	v_pk_mul_f32 v[42:43], v[42:43], v[102:103]
	v_pk_mul_f32 v[38:39], v[38:39], v[106:107]
	s_waitcnt lgkmcnt(0)
	v_pk_mul_f32 v[34:35], v[34:35], v[110:111]
	v_pk_mul_f32 v[32:33], v[32:33], v[108:109]
	v_pk_mul_f32 v[60:61], v[60:61], v[96:97]
	v_pk_mul_f32 v[56:57], v[56:57], v[100:101]
	v_pk_mul_f32 v[52:53], v[52:53], v[104:105]
	v_pk_mul_f32 v[62:63], v[62:63], v[98:99]
	v_pk_mul_f32 v[58:59], v[58:59], v[102:103]
	v_pk_mul_f32 v[54:55], v[54:55], v[106:107]
	v_pk_mul_f32 v[50:51], v[50:51], v[110:111]
	v_pk_mul_f32 v[48:49], v[48:49], v[108:109]
	v_pk_mul_f32 v[28:29], v[28:29], v[96:97]
	v_pk_mul_f32 v[24:25], v[24:25], v[100:101]
	v_pk_mul_f32 v[20:21], v[20:21], v[104:105]
	v_pk_mul_f32 v[30:31], v[30:31], v[98:99]
	v_pk_mul_f32 v[26:27], v[26:27], v[102:103]
	v_pk_mul_f32 v[22:23], v[22:23], v[106:107]
	v_pk_mul_f32 v[18:19], v[18:19], v[110:111]
	v_pk_mul_f32 v[16:17], v[16:17], v[108:109]
	v_pk_mul_f32 v[12:13], v[12:13], v[96:97]
	v_pk_mul_f32 v[8:9], v[8:9], v[100:101]
	v_pk_mul_f32 v[4:5], v[4:5], v[104:105]
	v_pk_mul_f32 v[14:15], v[14:15], v[98:99]
	v_pk_mul_f32 v[10:11], v[10:11], v[102:103]
	v_pk_mul_f32 v[6:7], v[6:7], v[106:107]
	v_pk_mul_f32 v[2:3], v[2:3], v[110:111]
	v_pk_mul_f32 v[0:1], v[0:1], v[108:109]
